# K-loop: barrier B 4 MFMAs early + s_setprio 3 for the tail MFMAs
# speedup vs baseline: 1.0918x; 1.0918x over previous
.LBB0_390:
	s_add_u32 s38, s42, 0x100
	s_addc_u32 s39, s43, 0
	s_add_i32 s4, 0, 0x10000
	s_cmp_eq_u32 s73, 12
	s_cselect_b32 s69, s29, s39
	s_cselect_b32 s68, vcc_lo, s38
	s_cselect_b32 s67, s37, s72
	s_cselect_b32 s66, vcc_hi, s59
	s_add_i32 s6, 0, 0x14000
	v_add_u32_e32 v142, s4, v251
	v_add_u32_e32 v158, s6, v251
	ds_read_b128 v[130:133], v142
	ds_read_b128 v[134:137], v142 offset:1024
	ds_read_b128 v[138:141], v142 offset:2048
	ds_read_b128 v[142:145], v142 offset:3072
	ds_read_b128 v[146:149], v158
	ds_read_b128 v[150:153], v158 offset:1024
	ds_read_b128 v[154:157], v158 offset:2048
	ds_read_b128 v[158:161], v158 offset:3072
	v_lshl_add_u64 v[194:195], s[42:43], 0, v[228:229]
	s_add_i32 m0, s75, 0xc000
	ds_read_b128 v[162:165], v244
	ds_read_b128 v[166:169], v244 offset:1024
	ds_read_b128 v[170:173], v244 offset:2048
	ds_read_b128 v[174:177], v244 offset:3072
	ds_read_b128 v[178:181], v244 offset:4096
	ds_read_b128 v[182:185], v244 offset:5120
	ds_read_b128 v[186:189], v244 offset:6144
	ds_read_b128 v[190:193], v244 offset:7168
	global_load_lds_dwordx4 v[194:195], off
	v_lshl_add_u64 v[194:195], s[42:43], 0, v[230:231]
	s_add_i32 m0, s75, 0xe000
	s_nop 0
	global_load_lds_dwordx4 v[194:195], off
	s_waitcnt vmcnt(8)
	s_waitcnt lgkmcnt(0)
	s_barrier
	s_setprio 1
	s_waitcnt lgkmcnt(0)
	v_mfma_f32_16x16x32_bf16 v[114:117], v[130:133], v[162:165], v[114:117]
	v_mfma_f32_16x16x32_bf16 v[122:125], v[138:141], v[162:165], v[122:125]
	v_mfma_f32_16x16x32_bf16 v[118:121], v[130:133], v[170:173], v[118:121]
	v_mfma_f32_16x16x32_bf16 v[126:129], v[138:141], v[170:173], v[126:129]
	v_mfma_f32_16x16x32_bf16 v[54:57], v[130:133], v[178:181], v[54:57]
	v_mfma_f32_16x16x32_bf16 v[70:73], v[138:141], v[178:181], v[70:73]
	v_mfma_f32_16x16x32_bf16 v[50:53], v[130:133], v[186:189], v[50:53]
	v_mfma_f32_16x16x32_bf16 v[66:69], v[138:141], v[186:189], v[66:69]
	v_mfma_f32_16x16x32_bf16 v[114:117], v[134:137], v[166:169], v[114:117]
	v_mfma_f32_16x16x32_bf16 v[122:125], v[142:145], v[166:169], v[122:125]
	v_mfma_f32_16x16x32_bf16 v[118:121], v[134:137], v[174:177], v[118:121]
	v_mfma_f32_16x16x32_bf16 v[126:129], v[142:145], v[174:177], v[126:129]
	v_mfma_f32_16x16x32_bf16 v[54:57], v[134:137], v[182:185], v[54:57]
	v_mfma_f32_16x16x32_bf16 v[70:73], v[142:145], v[182:185], v[70:73]
	v_mfma_f32_16x16x32_bf16 v[50:53], v[134:137], v[190:193], v[50:53]
	v_mfma_f32_16x16x32_bf16 v[66:69], v[142:145], v[190:193], v[66:69]
	s_setprio 0
	s_setprio 1
	v_mfma_f32_16x16x32_bf16 v[106:109], v[146:149], v[162:165], v[106:109]
	v_mfma_f32_16x16x32_bf16 v[42:45], v[154:157], v[162:165], v[42:45]
	v_mfma_f32_16x16x32_bf16 v[110:113], v[146:149], v[170:173], v[110:113]
	v_mfma_f32_16x16x32_bf16 v[46:49], v[154:157], v[170:173], v[46:49]
	v_mfma_f32_16x16x32_bf16 v[30:33], v[146:149], v[178:181], v[30:33]
	v_mfma_f32_16x16x32_bf16 v[14:17], v[154:157], v[178:181], v[14:17]
	v_mfma_f32_16x16x32_bf16 v[26:29], v[146:149], v[186:189], v[26:29]
	v_mfma_f32_16x16x32_bf16 v[10:13], v[154:157], v[186:189], v[10:13]
	v_mfma_f32_16x16x32_bf16 v[106:109], v[150:153], v[166:169], v[106:109]
	v_mfma_f32_16x16x32_bf16 v[42:45], v[158:161], v[166:169], v[42:45]
	v_mfma_f32_16x16x32_bf16 v[110:113], v[150:153], v[174:177], v[110:113]
	v_mfma_f32_16x16x32_bf16 v[46:49], v[158:161], v[174:177], v[46:49]
	s_barrier
	s_setprio 3
	v_mfma_f32_16x16x32_bf16 v[30:33], v[150:153], v[182:185], v[30:33]
	v_mfma_f32_16x16x32_bf16 v[14:17], v[158:161], v[182:185], v[14:17]
	v_mfma_f32_16x16x32_bf16 v[26:29], v[150:153], v[190:193], v[26:29]
	v_mfma_f32_16x16x32_bf16 v[10:13], v[158:161], v[190:193], v[10:13]
	s_setprio 0
	s_add_i32 s4, s4, s74
	v_lshl_add_u64 v[194:195], s[66:67], 0, v[0:1]
	s_mov_b32 m0, s4
	ds_read_b128 v[162:165], v244 offset:16384
	ds_read_b128 v[166:169], v244 offset:17408
	ds_read_b128 v[170:173], v244 offset:18432
	ds_read_b128 v[174:177], v244 offset:19456
	ds_read_b128 v[178:181], v244 offset:20480
	ds_read_b128 v[182:185], v244 offset:21504
	ds_read_b128 v[186:189], v244 offset:22528
	ds_read_b128 v[190:193], v244 offset:23552
	global_load_lds_dwordx4 v[194:195], off
	s_add_i32 m0, s4, 0x2000
	s_add_u32 s4, s66, 0x40000
	v_lshl_add_u64 v[196:197], s[66:67], 0, v[224:225]
	s_addc_u32 s5, s67, 0
	s_add_i32 s6, s6, s74
	global_load_lds_dwordx4 v[196:197], off
	v_lshl_add_u64 v[198:199], s[4:5], 0, v[0:1]
	s_mov_b32 m0, s6
	v_lshl_add_u64 v[200:201], s[68:69], 0, v[222:223]
	global_load_lds_dwordx4 v[198:199], off
	v_lshl_add_u64 v[198:199], s[4:5], 0, v[224:225]
	s_add_i32 m0, s6, 0x2000
	s_nop 0
	global_load_lds_dwordx4 v[198:199], off
	v_lshl_add_u64 v[198:199], s[68:69], 0, v[226:227]
	s_mov_b32 m0, s75
	s_nop 0
	global_load_lds_dwordx4 v[198:199], off
	s_mov_b32 m0, s76
	s_nop 0
	global_load_lds_dwordx4 v[200:201], off
	s_waitcnt vmcnt(8)
	s_waitcnt lgkmcnt(0)
	s_barrier
	s_setprio 1
	s_waitcnt lgkmcnt(0)
	v_mfma_f32_16x16x32_bf16 v[38:41], v[130:133], v[162:165], v[38:41]
	v_mfma_f32_16x16x32_bf16 v[62:65], v[138:141], v[162:165], v[62:65]
	v_mfma_f32_16x16x32_bf16 v[34:37], v[130:133], v[170:173], v[34:37]
	v_mfma_f32_16x16x32_bf16 v[58:61], v[138:141], v[170:173], v[58:61]
	v_mfma_f32_16x16x32_bf16 v[102:105], v[130:133], v[178:181], v[102:105]
	v_mfma_f32_16x16x32_bf16 v[98:101], v[138:141], v[178:181], v[98:101]
	v_mfma_f32_16x16x32_bf16 v[94:97], v[130:133], v[186:189], v[94:97]
	v_mfma_f32_16x16x32_bf16 v[90:93], v[138:141], v[186:189], v[90:93]
	v_mfma_f32_16x16x32_bf16 v[38:41], v[134:137], v[166:169], v[38:41]
	v_mfma_f32_16x16x32_bf16 v[62:65], v[142:145], v[166:169], v[62:65]
	v_mfma_f32_16x16x32_bf16 v[34:37], v[134:137], v[174:177], v[34:37]
	v_mfma_f32_16x16x32_bf16 v[58:61], v[142:145], v[174:177], v[58:61]
	v_mfma_f32_16x16x32_bf16 v[102:105], v[134:137], v[182:185], v[102:105]
	v_mfma_f32_16x16x32_bf16 v[98:101], v[142:145], v[182:185], v[98:101]
	v_mfma_f32_16x16x32_bf16 v[94:97], v[134:137], v[190:193], v[94:97]
	v_mfma_f32_16x16x32_bf16 v[90:93], v[142:145], v[190:193], v[90:93]
	s_setprio 0
	s_setprio 1
	v_mfma_f32_16x16x32_bf16 v[22:25], v[146:149], v[162:165], v[22:25]
	v_mfma_f32_16x16x32_bf16 v[6:9], v[154:157], v[162:165], v[6:9]
	v_mfma_f32_16x16x32_bf16 v[18:21], v[146:149], v[170:173], v[18:21]
	v_mfma_f32_16x16x32_bf16 v[2:5], v[154:157], v[170:173], v[2:5]
	v_mfma_f32_16x16x32_bf16 v[86:89], v[146:149], v[178:181], v[86:89]
	v_mfma_f32_16x16x32_bf16 v[82:85], v[154:157], v[178:181], v[82:85]
	v_mfma_f32_16x16x32_bf16 v[78:81], v[146:149], v[186:189], v[78:81]
	v_mfma_f32_16x16x32_bf16 v[74:77], v[154:157], v[186:189], v[74:77]
	v_mfma_f32_16x16x32_bf16 v[22:25], v[150:153], v[166:169], v[22:25]
	v_mfma_f32_16x16x32_bf16 v[6:9], v[158:161], v[166:169], v[6:9]
	v_mfma_f32_16x16x32_bf16 v[18:21], v[150:153], v[174:177], v[18:21]
	v_mfma_f32_16x16x32_bf16 v[2:5], v[158:161], v[174:177], v[2:5]
	s_barrier
	s_setprio 3
	v_mfma_f32_16x16x32_bf16 v[86:89], v[150:153], v[182:185], v[86:89]
	v_mfma_f32_16x16x32_bf16 v[82:85], v[158:161], v[182:185], v[82:85]
	v_mfma_f32_16x16x32_bf16 v[78:81], v[150:153], v[190:193], v[78:81]
	v_mfma_f32_16x16x32_bf16 v[74:77], v[158:161], v[190:193], v[74:77]
	s_setprio 0
	s_add_i32 s6, 0, 0x18000
	s_add_i32 s7, 0, 0x1c000
	v_add_u32_e32 v142, s6, v251
	v_add_u32_e32 v158, s7, v251
	ds_read_b128 v[130:133], v142
	ds_read_b128 v[134:137], v142 offset:1024
	ds_read_b128 v[138:141], v142 offset:2048
	ds_read_b128 v[142:145], v142 offset:3072
	ds_read_b128 v[146:149], v158
	ds_read_b128 v[150:153], v158 offset:1024
	ds_read_b128 v[154:157], v158 offset:2048
	ds_read_b128 v[158:161], v158 offset:3072
	s_add_u32 s4, s68, 0x2000
	s_addc_u32 s5, s69, 0
	s_mov_b32 m0, s77
	v_lshl_add_u64 v[202:203], s[4:5], 0, v[226:227]
	ds_read_b128 v[162:165], v244 offset:32768
	ds_read_b128 v[166:169], v244 offset:33792
	ds_read_b128 v[170:173], v244 offset:34816
	ds_read_b128 v[174:177], v244 offset:35840
	ds_read_b128 v[178:181], v244 offset:36864
	ds_read_b128 v[182:185], v244 offset:37888
	ds_read_b128 v[186:189], v244 offset:38912
	ds_read_b128 v[190:193], v244 offset:39936
	global_load_lds_dwordx4 v[202:203], off
	v_lshl_add_u64 v[202:203], s[4:5], 0, v[222:223]
	s_mov_b32 m0, s78
	s_nop 0
	global_load_lds_dwordx4 v[202:203], off
	s_waitcnt vmcnt(8)
	s_waitcnt lgkmcnt(0)
	s_barrier
	s_setprio 1
	s_waitcnt lgkmcnt(0)
	v_mfma_f32_16x16x32_bf16 v[114:117], v[130:133], v[162:165], v[114:117]
	v_mfma_f32_16x16x32_bf16 v[122:125], v[138:141], v[162:165], v[122:125]
	v_mfma_f32_16x16x32_bf16 v[118:121], v[130:133], v[170:173], v[118:121]
	v_mfma_f32_16x16x32_bf16 v[126:129], v[138:141], v[170:173], v[126:129]
	v_mfma_f32_16x16x32_bf16 v[54:57], v[130:133], v[178:181], v[54:57]
	v_mfma_f32_16x16x32_bf16 v[70:73], v[138:141], v[178:181], v[70:73]
	v_mfma_f32_16x16x32_bf16 v[50:53], v[130:133], v[186:189], v[50:53]
	v_mfma_f32_16x16x32_bf16 v[66:69], v[138:141], v[186:189], v[66:69]
	v_mfma_f32_16x16x32_bf16 v[114:117], v[134:137], v[166:169], v[114:117]
	v_mfma_f32_16x16x32_bf16 v[122:125], v[142:145], v[166:169], v[122:125]
	v_mfma_f32_16x16x32_bf16 v[118:121], v[134:137], v[174:177], v[118:121]
	v_mfma_f32_16x16x32_bf16 v[126:129], v[142:145], v[174:177], v[126:129]
	v_mfma_f32_16x16x32_bf16 v[54:57], v[134:137], v[182:185], v[54:57]
	v_mfma_f32_16x16x32_bf16 v[70:73], v[142:145], v[182:185], v[70:73]
	v_mfma_f32_16x16x32_bf16 v[50:53], v[134:137], v[190:193], v[50:53]
	v_mfma_f32_16x16x32_bf16 v[66:69], v[142:145], v[190:193], v[66:69]
	s_setprio 0
	s_setprio 1
	v_mfma_f32_16x16x32_bf16 v[106:109], v[146:149], v[162:165], v[106:109]
	v_mfma_f32_16x16x32_bf16 v[42:45], v[154:157], v[162:165], v[42:45]
	v_mfma_f32_16x16x32_bf16 v[110:113], v[146:149], v[170:173], v[110:113]
	v_mfma_f32_16x16x32_bf16 v[46:49], v[154:157], v[170:173], v[46:49]
	v_mfma_f32_16x16x32_bf16 v[30:33], v[146:149], v[178:181], v[30:33]
	v_mfma_f32_16x16x32_bf16 v[14:17], v[154:157], v[178:181], v[14:17]
	v_mfma_f32_16x16x32_bf16 v[26:29], v[146:149], v[186:189], v[26:29]
	v_mfma_f32_16x16x32_bf16 v[10:13], v[154:157], v[186:189], v[10:13]
	v_mfma_f32_16x16x32_bf16 v[106:109], v[150:153], v[166:169], v[106:109]
	v_mfma_f32_16x16x32_bf16 v[42:45], v[158:161], v[166:169], v[42:45]
	v_mfma_f32_16x16x32_bf16 v[110:113], v[150:153], v[174:177], v[110:113]
	v_mfma_f32_16x16x32_bf16 v[46:49], v[158:161], v[174:177], v[46:49]
	s_barrier
	s_setprio 3
	v_mfma_f32_16x16x32_bf16 v[30:33], v[150:153], v[182:185], v[30:33]
	v_mfma_f32_16x16x32_bf16 v[14:17], v[158:161], v[182:185], v[14:17]
	v_mfma_f32_16x16x32_bf16 v[26:29], v[150:153], v[190:193], v[26:29]
	v_mfma_f32_16x16x32_bf16 v[10:13], v[158:161], v[190:193], v[10:13]
	s_setprio 0
	s_add_i32 s4, s6, s74
	v_lshl_add_u64 v[194:195], v[194:195], 0, s[82:83]
	s_mov_b32 m0, s4
	ds_read_b128 v[162:165], v244 offset:49152
	ds_read_b128 v[166:169], v244 offset:50176
	ds_read_b128 v[170:173], v244 offset:51200
	ds_read_b128 v[174:177], v244 offset:52224
	ds_read_b128 v[178:181], v244 offset:53248
	ds_read_b128 v[182:185], v244 offset:54272
	ds_read_b128 v[186:189], v244 offset:55296
	ds_read_b128 v[190:193], v244 offset:56320
	global_load_lds_dwordx4 v[194:195], off
	s_add_i32 m0, s4, 0x2000
	s_add_u32 s4, s66, 0x40080
	v_lshl_add_u64 v[194:195], v[196:197], 0, s[82:83]
	s_addc_u32 s5, s67, 0
	s_add_i32 s6, s7, s74
	global_load_lds_dwordx4 v[194:195], off
	v_lshl_add_u64 v[194:195], s[4:5], 0, v[0:1]
	s_mov_b32 m0, s6
	s_nop 0
	global_load_lds_dwordx4 v[194:195], off
	v_lshl_add_u64 v[194:195], s[4:5], 0, v[224:225]
	s_add_i32 m0, s6, 0x2000
	s_nop 0
	global_load_lds_dwordx4 v[194:195], off
	v_lshl_add_u64 v[194:195], v[198:199], 0, s[82:83]
	s_mov_b32 m0, s94
	s_nop 0
	global_load_lds_dwordx4 v[194:195], off
	v_lshl_add_u64 v[194:195], v[200:201], 0, s[82:83]
	s_mov_b32 m0, s95
	s_nop 0
	global_load_lds_dwordx4 v[194:195], off
	s_waitcnt vmcnt(8)
	s_waitcnt lgkmcnt(0)
	s_barrier
	s_setprio 1
	s_waitcnt lgkmcnt(0)
	v_mfma_f32_16x16x32_bf16 v[38:41], v[130:133], v[162:165], v[38:41]
	v_mfma_f32_16x16x32_bf16 v[62:65], v[138:141], v[162:165], v[62:65]
	v_mfma_f32_16x16x32_bf16 v[34:37], v[130:133], v[170:173], v[34:37]
	v_mfma_f32_16x16x32_bf16 v[58:61], v[138:141], v[170:173], v[58:61]
	v_mfma_f32_16x16x32_bf16 v[102:105], v[130:133], v[178:181], v[102:105]
	v_mfma_f32_16x16x32_bf16 v[98:101], v[138:141], v[178:181], v[98:101]
	v_mfma_f32_16x16x32_bf16 v[94:97], v[130:133], v[186:189], v[94:97]
	v_mfma_f32_16x16x32_bf16 v[90:93], v[138:141], v[186:189], v[90:93]
	v_mfma_f32_16x16x32_bf16 v[38:41], v[134:137], v[166:169], v[38:41]
	v_mfma_f32_16x16x32_bf16 v[62:65], v[142:145], v[166:169], v[62:65]
	v_mfma_f32_16x16x32_bf16 v[34:37], v[134:137], v[174:177], v[34:37]
	v_mfma_f32_16x16x32_bf16 v[58:61], v[142:145], v[174:177], v[58:61]
	v_mfma_f32_16x16x32_bf16 v[102:105], v[134:137], v[182:185], v[102:105]
	v_mfma_f32_16x16x32_bf16 v[98:101], v[142:145], v[182:185], v[98:101]
	v_mfma_f32_16x16x32_bf16 v[94:97], v[134:137], v[190:193], v[94:97]
	v_mfma_f32_16x16x32_bf16 v[90:93], v[142:145], v[190:193], v[90:93]
	s_setprio 0
	s_setprio 1
	v_mfma_f32_16x16x32_bf16 v[22:25], v[146:149], v[162:165], v[22:25]
	v_mfma_f32_16x16x32_bf16 v[6:9], v[154:157], v[162:165], v[6:9]
	v_mfma_f32_16x16x32_bf16 v[18:21], v[146:149], v[170:173], v[18:21]
	v_mfma_f32_16x16x32_bf16 v[2:5], v[154:157], v[170:173], v[2:5]
	v_mfma_f32_16x16x32_bf16 v[86:89], v[146:149], v[178:181], v[86:89]
	v_mfma_f32_16x16x32_bf16 v[82:85], v[154:157], v[178:181], v[82:85]
	v_mfma_f32_16x16x32_bf16 v[78:81], v[146:149], v[186:189], v[78:81]
	v_mfma_f32_16x16x32_bf16 v[74:77], v[154:157], v[186:189], v[74:77]
	v_mfma_f32_16x16x32_bf16 v[22:25], v[150:153], v[166:169], v[22:25]
	v_mfma_f32_16x16x32_bf16 v[6:9], v[158:161], v[166:169], v[6:9]
	v_mfma_f32_16x16x32_bf16 v[18:21], v[150:153], v[174:177], v[18:21]
	v_mfma_f32_16x16x32_bf16 v[2:5], v[158:161], v[174:177], v[2:5]
	s_barrier
	s_setprio 3
	v_mfma_f32_16x16x32_bf16 v[86:89], v[150:153], v[182:185], v[86:89]
	v_mfma_f32_16x16x32_bf16 v[82:85], v[158:161], v[182:185], v[82:85]
	v_mfma_f32_16x16x32_bf16 v[78:81], v[150:153], v[190:193], v[78:81]
	v_mfma_f32_16x16x32_bf16 v[74:77], v[158:161], v[190:193], v[74:77]
	s_setprio 0
	s_add_i32 s73, s73, 2
	s_add_u32 s59, s59, 0x100
	s_addc_u32 s72, s72, 0
	s_cmp_gt_u32 s73, 13
	s_mov_b64 s[42:43], s[38:39]
	s_cbranch_scc0 .LBB0_390
	s_and_b64 vcc, exec, s[50:51]
	s_cbranch_vccz .LBB0_393
	s_barrier

.LBB0_452:
	s_add_i32 s59, s34, 2
	s_add_u32 s4, s30, 0x80
	s_addc_u32 s5, s31, 0
	s_add_i32 s6, 0, 0x10000
	s_cmp_eq_u32 s53, s34
	s_cselect_b32 s35, s27, s5
	s_cselect_b32 s34, s26, s4
	s_cselect_b32 s5, s29, s43
	s_cselect_b32 s4, s28, s42
	s_add_i32 s7, 0, 0x14000
	v_add_u32_e32 v142, s6, v184
	v_add_u32_e32 v168, s7, v184
	ds_read_b128 v[130:133], v142
	ds_read_b128 v[134:137], v142 offset:1024
	ds_read_b128 v[138:141], v142 offset:2048
	ds_read_b128 v[142:145], v142 offset:3072
	ds_read_b128 v[146:149], v168
	ds_read_b128 v[150:153], v168 offset:1024
	ds_read_b128 v[154:157], v168 offset:2048
	ds_read_b128 v[168:171], v168 offset:3072
	v_lshl_add_u64 v[180:181], s[30:31], 0, v[164:165]
	s_add_i32 m0, s38, 0xc000
	ds_read_b128 v[172:175], v187
	ds_read_b128 v[176:179], v187 offset:1024
	ds_read_b128 v[188:191], v187 offset:2048
	ds_read_b128 v[192:195], v187 offset:3072
	ds_read_b128 v[196:199], v187 offset:4096
	ds_read_b128 v[200:203], v187 offset:5120
	ds_read_b128 v[204:207], v187 offset:6144
	ds_read_b128 v[222:225], v187 offset:7168
	global_load_lds_dwordx4 v[180:181], off
	v_lshl_add_u64 v[180:181], s[30:31], 0, v[166:167]
	s_add_i32 m0, s38, 0xe000
	s_nop 0
	global_load_lds_dwordx4 v[180:181], off
	s_waitcnt vmcnt(8)
	s_waitcnt lgkmcnt(0)
	s_barrier
	s_setprio 1
	s_waitcnt lgkmcnt(0)
	v_mfma_f32_16x16x32_bf16 v[126:129], v[130:133], v[172:175], v[126:129]
	v_mfma_f32_16x16x32_bf16 v[122:125], v[138:141], v[172:175], v[122:125]
	v_mfma_f32_16x16x32_bf16 v[110:113], v[130:133], v[188:191], v[110:113]
	v_mfma_f32_16x16x32_bf16 v[106:109], v[138:141], v[188:191], v[106:109]
	v_mfma_f32_16x16x32_bf16 v[98:101], v[130:133], v[196:199], v[98:101]
	v_mfma_f32_16x16x32_bf16 v[90:93], v[138:141], v[196:199], v[90:93]
	v_mfma_f32_16x16x32_bf16 v[82:85], v[130:133], v[204:207], v[82:85]
	v_mfma_f32_16x16x32_bf16 v[74:77], v[138:141], v[204:207], v[74:77]
	v_mfma_f32_16x16x32_bf16 v[126:129], v[134:137], v[176:179], v[126:129]
	v_mfma_f32_16x16x32_bf16 v[122:125], v[142:145], v[176:179], v[122:125]
	v_mfma_f32_16x16x32_bf16 v[110:113], v[134:137], v[192:195], v[110:113]
	v_mfma_f32_16x16x32_bf16 v[106:109], v[142:145], v[192:195], v[106:109]
	v_mfma_f32_16x16x32_bf16 v[98:101], v[134:137], v[200:203], v[98:101]
	v_mfma_f32_16x16x32_bf16 v[90:93], v[142:145], v[200:203], v[90:93]
	v_mfma_f32_16x16x32_bf16 v[82:85], v[134:137], v[222:225], v[82:85]
	v_mfma_f32_16x16x32_bf16 v[74:77], v[142:145], v[222:225], v[74:77]
	s_setprio 0
	s_setprio 1
	v_mfma_f32_16x16x32_bf16 v[118:121], v[146:149], v[172:175], v[118:121]
	v_mfma_f32_16x16x32_bf16 v[114:117], v[154:157], v[172:175], v[114:117]
	v_mfma_f32_16x16x32_bf16 v[102:105], v[146:149], v[188:191], v[102:105]
	v_mfma_f32_16x16x32_bf16 v[94:97], v[154:157], v[188:191], v[94:97]
	v_mfma_f32_16x16x32_bf16 v[86:89], v[146:149], v[196:199], v[86:89]
	v_mfma_f32_16x16x32_bf16 v[78:81], v[154:157], v[196:199], v[78:81]
	v_mfma_f32_16x16x32_bf16 v[70:73], v[146:149], v[204:207], v[70:73]
	v_mfma_f32_16x16x32_bf16 v[66:69], v[154:157], v[204:207], v[66:69]
	v_mfma_f32_16x16x32_bf16 v[118:121], v[150:153], v[176:179], v[118:121]
	v_mfma_f32_16x16x32_bf16 v[114:117], v[168:171], v[176:179], v[114:117]
	v_mfma_f32_16x16x32_bf16 v[102:105], v[150:153], v[192:195], v[102:105]
	v_mfma_f32_16x16x32_bf16 v[94:97], v[168:171], v[192:195], v[94:97]
	s_barrier
	s_setprio 3
	v_mfma_f32_16x16x32_bf16 v[86:89], v[150:153], v[200:203], v[86:89]
	v_mfma_f32_16x16x32_bf16 v[78:81], v[168:171], v[200:203], v[78:81]
	v_mfma_f32_16x16x32_bf16 v[70:73], v[150:153], v[222:225], v[70:73]
	v_mfma_f32_16x16x32_bf16 v[66:69], v[168:171], v[222:225], v[66:69]
	s_setprio 0
	s_add_i32 s6, s6, s37
	v_lshl_add_u64 v[180:181], s[4:5], 0, v[0:1]
	s_mov_b32 m0, s6
	ds_read_b128 v[172:175], v187 offset:16384
	ds_read_b128 v[176:179], v187 offset:17408
	ds_read_b128 v[188:191], v187 offset:18432
	ds_read_b128 v[192:195], v187 offset:19456
	ds_read_b128 v[196:199], v187 offset:20480
	ds_read_b128 v[200:203], v187 offset:21504
	ds_read_b128 v[204:207], v187 offset:22528
	ds_read_b128 v[222:225], v187 offset:23552
	global_load_lds_dwordx4 v[180:181], off
	s_add_i32 m0, s6, 0x2000
	v_lshl_add_u64 v[208:209], s[4:5], 0, v[160:161]
	s_add_u32 s4, s4, s84
	s_addc_u32 s5, s5, 0
	s_add_i32 s6, s7, s37
	global_load_lds_dwordx4 v[208:209], off
	v_lshl_add_u64 v[226:227], s[4:5], 0, v[0:1]
	s_mov_b32 m0, s6
	v_lshl_add_u64 v[228:229], s[4:5], 0, v[160:161]
	global_load_lds_dwordx4 v[226:227], off
	s_add_i32 m0, s6, 0x2000
	v_lshl_add_u64 v[230:231], s[34:35], 0, v[162:163]
	global_load_lds_dwordx4 v[228:229], off
	s_mov_b32 m0, s38
	v_lshl_add_u64 v[232:233], s[34:35], 0, v[158:159]
	global_load_lds_dwordx4 v[230:231], off
	s_mov_b32 m0, s39
	s_nop 0
	global_load_lds_dwordx4 v[232:233], off
	s_waitcnt vmcnt(8)
	s_waitcnt lgkmcnt(0)
	s_barrier
	s_setprio 1
	s_waitcnt lgkmcnt(0)
	v_mfma_f32_16x16x32_bf16 v[62:65], v[130:133], v[172:175], v[62:65]
	v_mfma_f32_16x16x32_bf16 v[58:61], v[138:141], v[172:175], v[58:61]
	v_mfma_f32_16x16x32_bf16 v[46:49], v[130:133], v[188:191], v[46:49]
	v_mfma_f32_16x16x32_bf16 v[42:45], v[138:141], v[188:191], v[42:45]
	v_mfma_f32_16x16x32_bf16 v[34:37], v[130:133], v[196:199], v[34:37]
	v_mfma_f32_16x16x32_bf16 v[26:29], v[138:141], v[196:199], v[26:29]
	v_mfma_f32_16x16x32_bf16 v[18:21], v[130:133], v[204:207], v[18:21]
	v_mfma_f32_16x16x32_bf16 v[10:13], v[138:141], v[204:207], v[10:13]
	v_mfma_f32_16x16x32_bf16 v[62:65], v[134:137], v[176:179], v[62:65]
	v_mfma_f32_16x16x32_bf16 v[58:61], v[142:145], v[176:179], v[58:61]
	v_mfma_f32_16x16x32_bf16 v[46:49], v[134:137], v[192:195], v[46:49]
	v_mfma_f32_16x16x32_bf16 v[42:45], v[142:145], v[192:195], v[42:45]
	v_mfma_f32_16x16x32_bf16 v[34:37], v[134:137], v[200:203], v[34:37]
	v_mfma_f32_16x16x32_bf16 v[26:29], v[142:145], v[200:203], v[26:29]
	v_mfma_f32_16x16x32_bf16 v[18:21], v[134:137], v[222:225], v[18:21]
	v_mfma_f32_16x16x32_bf16 v[10:13], v[142:145], v[222:225], v[10:13]
	s_setprio 0
	s_setprio 1
	v_mfma_f32_16x16x32_bf16 v[54:57], v[146:149], v[172:175], v[54:57]
	v_mfma_f32_16x16x32_bf16 v[50:53], v[154:157], v[172:175], v[50:53]
	v_mfma_f32_16x16x32_bf16 v[38:41], v[146:149], v[188:191], v[38:41]
	v_mfma_f32_16x16x32_bf16 v[30:33], v[154:157], v[188:191], v[30:33]
	v_mfma_f32_16x16x32_bf16 v[22:25], v[146:149], v[196:199], v[22:25]
	v_mfma_f32_16x16x32_bf16 v[14:17], v[154:157], v[196:199], v[14:17]
	v_mfma_f32_16x16x32_bf16 v[6:9], v[146:149], v[204:207], v[6:9]
	v_mfma_f32_16x16x32_bf16 v[2:5], v[154:157], v[204:207], v[2:5]
	v_mfma_f32_16x16x32_bf16 v[54:57], v[150:153], v[176:179], v[54:57]
	v_mfma_f32_16x16x32_bf16 v[50:53], v[168:171], v[176:179], v[50:53]
	v_mfma_f32_16x16x32_bf16 v[38:41], v[150:153], v[192:195], v[38:41]
	v_mfma_f32_16x16x32_bf16 v[30:33], v[168:171], v[192:195], v[30:33]
	s_barrier
	s_setprio 3
	v_mfma_f32_16x16x32_bf16 v[22:25], v[150:153], v[200:203], v[22:25]
	v_mfma_f32_16x16x32_bf16 v[14:17], v[168:171], v[200:203], v[14:17]
	v_mfma_f32_16x16x32_bf16 v[6:9], v[150:153], v[222:225], v[6:9]
	v_mfma_f32_16x16x32_bf16 v[2:5], v[168:171], v[222:225], v[2:5]
	s_setprio 0
	s_add_i32 s6, 0, 0x18000
	s_add_i32 s7, 0, 0x1c000
	v_add_u32_e32 v142, s6, v184
	v_add_u32_e32 v168, s7, v184
	ds_read_b128 v[130:133], v142
	ds_read_b128 v[134:137], v142 offset:1024
	ds_read_b128 v[138:141], v142 offset:2048
	ds_read_b128 v[142:145], v142 offset:3072
	ds_read_b128 v[146:149], v168
	ds_read_b128 v[150:153], v168 offset:1024
	ds_read_b128 v[154:157], v168 offset:2048
	ds_read_b128 v[168:171], v168 offset:3072
	s_add_u32 s4, s34, s84
	s_addc_u32 s5, s35, 0
	s_mov_b32 m0, s45
	v_lshl_add_u64 v[234:235], s[4:5], 0, v[162:163]
	ds_read_b128 v[172:175], v187 offset:32768
	ds_read_b128 v[176:179], v187 offset:33792
	ds_read_b128 v[188:191], v187 offset:34816
	ds_read_b128 v[192:195], v187 offset:35840
	ds_read_b128 v[196:199], v187 offset:36864
	ds_read_b128 v[200:203], v187 offset:37888
	ds_read_b128 v[204:207], v187 offset:38912
	ds_read_b128 v[222:225], v187 offset:39936
	global_load_lds_dwordx4 v[234:235], off
	v_lshl_add_u64 v[234:235], s[4:5], 0, v[158:159]
	s_mov_b32 m0, s46
	s_nop 0
	global_load_lds_dwordx4 v[234:235], off
	s_waitcnt vmcnt(8)
	s_waitcnt lgkmcnt(0)
	s_barrier
	s_setprio 1
	s_waitcnt lgkmcnt(0)
	v_mfma_f32_16x16x32_bf16 v[126:129], v[130:133], v[172:175], v[126:129]
	v_mfma_f32_16x16x32_bf16 v[122:125], v[138:141], v[172:175], v[122:125]
	v_mfma_f32_16x16x32_bf16 v[110:113], v[130:133], v[188:191], v[110:113]
	v_mfma_f32_16x16x32_bf16 v[106:109], v[138:141], v[188:191], v[106:109]
	v_mfma_f32_16x16x32_bf16 v[98:101], v[130:133], v[196:199], v[98:101]
	v_mfma_f32_16x16x32_bf16 v[90:93], v[138:141], v[196:199], v[90:93]
	v_mfma_f32_16x16x32_bf16 v[82:85], v[130:133], v[204:207], v[82:85]
	v_mfma_f32_16x16x32_bf16 v[74:77], v[138:141], v[204:207], v[74:77]
	v_mfma_f32_16x16x32_bf16 v[126:129], v[134:137], v[176:179], v[126:129]
	v_mfma_f32_16x16x32_bf16 v[122:125], v[142:145], v[176:179], v[122:125]
	v_mfma_f32_16x16x32_bf16 v[110:113], v[134:137], v[192:195], v[110:113]
	v_mfma_f32_16x16x32_bf16 v[106:109], v[142:145], v[192:195], v[106:109]
	v_mfma_f32_16x16x32_bf16 v[98:101], v[134:137], v[200:203], v[98:101]
	v_mfma_f32_16x16x32_bf16 v[90:93], v[142:145], v[200:203], v[90:93]
	v_mfma_f32_16x16x32_bf16 v[82:85], v[134:137], v[222:225], v[82:85]
	v_mfma_f32_16x16x32_bf16 v[74:77], v[142:145], v[222:225], v[74:77]
	s_setprio 0
	s_setprio 1
	v_mfma_f32_16x16x32_bf16 v[118:121], v[146:149], v[172:175], v[118:121]
	v_mfma_f32_16x16x32_bf16 v[114:117], v[154:157], v[172:175], v[114:117]
	v_mfma_f32_16x16x32_bf16 v[102:105], v[146:149], v[188:191], v[102:105]
	v_mfma_f32_16x16x32_bf16 v[94:97], v[154:157], v[188:191], v[94:97]
	v_mfma_f32_16x16x32_bf16 v[86:89], v[146:149], v[196:199], v[86:89]
	v_mfma_f32_16x16x32_bf16 v[78:81], v[154:157], v[196:199], v[78:81]
	v_mfma_f32_16x16x32_bf16 v[70:73], v[146:149], v[204:207], v[70:73]
	v_mfma_f32_16x16x32_bf16 v[66:69], v[154:157], v[204:207], v[66:69]
	v_mfma_f32_16x16x32_bf16 v[118:121], v[150:153], v[176:179], v[118:121]
	v_mfma_f32_16x16x32_bf16 v[114:117], v[168:171], v[176:179], v[114:117]
	v_mfma_f32_16x16x32_bf16 v[102:105], v[150:153], v[192:195], v[102:105]
	v_mfma_f32_16x16x32_bf16 v[94:97], v[168:171], v[192:195], v[94:97]
	s_barrier
	s_setprio 3
	v_mfma_f32_16x16x32_bf16 v[86:89], v[150:153], v[200:203], v[86:89]
	v_mfma_f32_16x16x32_bf16 v[78:81], v[168:171], v[200:203], v[78:81]
	v_mfma_f32_16x16x32_bf16 v[70:73], v[150:153], v[222:225], v[70:73]
	v_mfma_f32_16x16x32_bf16 v[66:69], v[168:171], v[222:225], v[66:69]
	s_setprio 0
	s_add_i32 s4, s6, s37
	v_lshl_add_u64 v[180:181], v[180:181], 0, s[82:83]
	s_mov_b32 m0, s4
	ds_read_b128 v[172:175], v187 offset:49152
	ds_read_b128 v[176:179], v187 offset:50176
	ds_read_b128 v[188:191], v187 offset:51200
	ds_read_b128 v[192:195], v187 offset:52224
	ds_read_b128 v[196:199], v187 offset:53248
	ds_read_b128 v[200:203], v187 offset:54272
	ds_read_b128 v[204:207], v187 offset:55296
	ds_read_b128 v[222:225], v187 offset:56320
	global_load_lds_dwordx4 v[180:181], off
	v_lshl_add_u64 v[180:181], v[208:209], 0, s[82:83]
	s_add_i32 m0, s4, 0x2000
	s_add_i32 s4, s7, s37
	global_load_lds_dwordx4 v[180:181], off
	v_lshl_add_u64 v[180:181], v[226:227], 0, s[82:83]
	s_mov_b32 m0, s4
	s_nop 0
	global_load_lds_dwordx4 v[180:181], off
	v_lshl_add_u64 v[180:181], v[228:229], 0, s[82:83]
	s_add_i32 m0, s4, 0x2000
	s_nop 0
	global_load_lds_dwordx4 v[180:181], off
	v_lshl_add_u64 v[180:181], v[230:231], 0, s[82:83]
	s_mov_b32 m0, s51
	s_nop 0
	global_load_lds_dwordx4 v[180:181], off
	v_lshl_add_u64 v[180:181], v[232:233], 0, s[82:83]
	s_mov_b32 m0, s52
	s_nop 0
	global_load_lds_dwordx4 v[180:181], off
	s_waitcnt vmcnt(8)
	s_waitcnt lgkmcnt(0)
	s_barrier
	s_setprio 1
	s_waitcnt lgkmcnt(0)
	v_mfma_f32_16x16x32_bf16 v[62:65], v[130:133], v[172:175], v[62:65]
	v_mfma_f32_16x16x32_bf16 v[58:61], v[138:141], v[172:175], v[58:61]
	v_mfma_f32_16x16x32_bf16 v[46:49], v[130:133], v[188:191], v[46:49]
	v_mfma_f32_16x16x32_bf16 v[42:45], v[138:141], v[188:191], v[42:45]
	v_mfma_f32_16x16x32_bf16 v[34:37], v[130:133], v[196:199], v[34:37]
	v_mfma_f32_16x16x32_bf16 v[26:29], v[138:141], v[196:199], v[26:29]
	v_mfma_f32_16x16x32_bf16 v[18:21], v[130:133], v[204:207], v[18:21]
	v_mfma_f32_16x16x32_bf16 v[10:13], v[138:141], v[204:207], v[10:13]
	v_mfma_f32_16x16x32_bf16 v[62:65], v[134:137], v[176:179], v[62:65]
	v_mfma_f32_16x16x32_bf16 v[58:61], v[142:145], v[176:179], v[58:61]
	v_mfma_f32_16x16x32_bf16 v[46:49], v[134:137], v[192:195], v[46:49]
	v_mfma_f32_16x16x32_bf16 v[42:45], v[142:145], v[192:195], v[42:45]
	v_mfma_f32_16x16x32_bf16 v[34:37], v[134:137], v[200:203], v[34:37]
	v_mfma_f32_16x16x32_bf16 v[26:29], v[142:145], v[200:203], v[26:29]
	v_mfma_f32_16x16x32_bf16 v[18:21], v[134:137], v[222:225], v[18:21]
	v_mfma_f32_16x16x32_bf16 v[10:13], v[142:145], v[222:225], v[10:13]
	s_setprio 0
	s_setprio 1
	v_mfma_f32_16x16x32_bf16 v[54:57], v[146:149], v[172:175], v[54:57]
	v_mfma_f32_16x16x32_bf16 v[50:53], v[154:157], v[172:175], v[50:53]
	v_mfma_f32_16x16x32_bf16 v[38:41], v[146:149], v[188:191], v[38:41]
	v_mfma_f32_16x16x32_bf16 v[30:33], v[154:157], v[188:191], v[30:33]
	v_mfma_f32_16x16x32_bf16 v[22:25], v[146:149], v[196:199], v[22:25]
	v_mfma_f32_16x16x32_bf16 v[14:17], v[154:157], v[196:199], v[14:17]
	v_mfma_f32_16x16x32_bf16 v[6:9], v[146:149], v[204:207], v[6:9]
	v_mfma_f32_16x16x32_bf16 v[2:5], v[154:157], v[204:207], v[2:5]
	v_mfma_f32_16x16x32_bf16 v[54:57], v[150:153], v[176:179], v[54:57]
	v_mfma_f32_16x16x32_bf16 v[50:53], v[168:171], v[176:179], v[50:53]
	v_mfma_f32_16x16x32_bf16 v[38:41], v[150:153], v[192:195], v[38:41]
	v_mfma_f32_16x16x32_bf16 v[30:33], v[168:171], v[192:195], v[30:33]
	s_barrier
	s_setprio 3
	v_mfma_f32_16x16x32_bf16 v[22:25], v[150:153], v[200:203], v[22:25]
	v_mfma_f32_16x16x32_bf16 v[14:17], v[168:171], v[200:203], v[14:17]
	v_mfma_f32_16x16x32_bf16 v[6:9], v[150:153], v[222:225], v[6:9]
	v_mfma_f32_16x16x32_bf16 v[2:5], v[168:171], v[222:225], v[2:5]
	s_setprio 0
	s_add_u32 s30, s30, 0x100
	s_addc_u32 s31, s31, 0
	s_add_u32 s42, s42, 0x100
	s_addc_u32 s43, s43, 0
	s_cmp_ge_u32 s59, s48
	s_mov_b32 s34, s59
	s_cbranch_scc0 .LBB0_452
	s_and_b64 vcc, exec, s[24:25]
	s_cbranch_vccz .LBB0_455
	s_barrier

.LBB0_489:
	s_add_u32 s4, s30, 0xfffc0080
	s_addc_u32 s5, s31, -1
	s_add_i32 s6, 0, 0x10000
	s_cmp_eq_u32 s59, 12
	s_cselect_b32 s37, s25, s5
	s_cselect_b32 s36, s66, s4
	s_cselect_b32 s35, s23, s69
	s_cselect_b32 s34, s67, s68
	s_add_i32 s7, 0, 0x14000
	v_add_u32_e32 v156, s6, v146
	v_add_u32_e32 v172, s7, v146
	ds_read_b128 v[140:143], v156
	ds_read_b128 v[148:151], v156 offset:1024
	ds_read_b128 v[152:155], v156 offset:2048
	ds_read_b128 v[156:159], v156 offset:3072
	ds_read_b128 v[160:163], v172
	ds_read_b128 v[164:167], v172 offset:1024
	ds_read_b128 v[168:171], v172 offset:2048
	ds_read_b128 v[172:175], v172 offset:3072
	v_lshl_add_u64 v[208:209], s[30:31], 0, v[136:137]
	s_add_i32 m0, s43, 0xc000
	ds_read_b128 v[176:179], v147
	ds_read_b128 v[180:183], v147 offset:1024
	ds_read_b128 v[184:187], v147 offset:2048
	ds_read_b128 v[188:191], v147 offset:3072
	ds_read_b128 v[192:195], v147 offset:4096
	ds_read_b128 v[196:199], v147 offset:5120
	ds_read_b128 v[200:203], v147 offset:6144
	ds_read_b128 v[204:207], v147 offset:7168
	global_load_lds_dwordx4 v[208:209], off
	v_lshl_add_u64 v[208:209], s[30:31], 0, v[138:139]
	s_add_i32 m0, s43, 0xe000
	s_nop 0
	global_load_lds_dwordx4 v[208:209], off
	s_waitcnt vmcnt(8)
	s_waitcnt lgkmcnt(0)
	s_barrier
	s_setprio 1
	s_waitcnt lgkmcnt(0)
	v_mfma_f32_16x16x32_bf16 v[126:129], v[140:143], v[176:179], v[126:129]
	v_mfma_f32_16x16x32_bf16 v[122:125], v[152:155], v[176:179], v[122:125]
	v_mfma_f32_16x16x32_bf16 v[118:121], v[140:143], v[184:187], v[118:121]
	v_mfma_f32_16x16x32_bf16 v[110:113], v[152:155], v[184:187], v[110:113]
	v_mfma_f32_16x16x32_bf16 v[102:105], v[140:143], v[192:195], v[102:105]
	v_mfma_f32_16x16x32_bf16 v[94:97], v[152:155], v[192:195], v[94:97]
	v_mfma_f32_16x16x32_bf16 v[86:89], v[140:143], v[200:203], v[86:89]
	v_mfma_f32_16x16x32_bf16 v[78:81], v[152:155], v[200:203], v[78:81]
	v_mfma_f32_16x16x32_bf16 v[126:129], v[148:151], v[180:183], v[126:129]
	v_mfma_f32_16x16x32_bf16 v[122:125], v[156:159], v[180:183], v[122:125]
	v_mfma_f32_16x16x32_bf16 v[118:121], v[148:151], v[188:191], v[118:121]
	v_mfma_f32_16x16x32_bf16 v[110:113], v[156:159], v[188:191], v[110:113]
	v_mfma_f32_16x16x32_bf16 v[102:105], v[148:151], v[196:199], v[102:105]
	v_mfma_f32_16x16x32_bf16 v[94:97], v[156:159], v[196:199], v[94:97]
	v_mfma_f32_16x16x32_bf16 v[86:89], v[148:151], v[204:207], v[86:89]
	v_mfma_f32_16x16x32_bf16 v[78:81], v[156:159], v[204:207], v[78:81]
	s_setprio 0
	s_setprio 1
	v_mfma_f32_16x16x32_bf16 v[114:117], v[160:163], v[176:179], v[114:117]
	v_mfma_f32_16x16x32_bf16 v[106:109], v[168:171], v[176:179], v[106:109]
	v_mfma_f32_16x16x32_bf16 v[98:101], v[160:163], v[184:187], v[98:101]
	v_mfma_f32_16x16x32_bf16 v[90:93], v[168:171], v[184:187], v[90:93]
	v_mfma_f32_16x16x32_bf16 v[82:85], v[160:163], v[192:195], v[82:85]
	v_mfma_f32_16x16x32_bf16 v[74:77], v[168:171], v[192:195], v[74:77]
	v_mfma_f32_16x16x32_bf16 v[70:73], v[160:163], v[200:203], v[70:73]
	v_mfma_f32_16x16x32_bf16 v[66:69], v[168:171], v[200:203], v[66:69]
	v_mfma_f32_16x16x32_bf16 v[114:117], v[164:167], v[180:183], v[114:117]
	v_mfma_f32_16x16x32_bf16 v[106:109], v[172:175], v[180:183], v[106:109]
	v_mfma_f32_16x16x32_bf16 v[98:101], v[164:167], v[188:191], v[98:101]
	v_mfma_f32_16x16x32_bf16 v[90:93], v[172:175], v[188:191], v[90:93]
	s_barrier
	s_setprio 3
	v_mfma_f32_16x16x32_bf16 v[82:85], v[164:167], v[196:199], v[82:85]
	v_mfma_f32_16x16x32_bf16 v[74:77], v[172:175], v[196:199], v[74:77]
	v_mfma_f32_16x16x32_bf16 v[70:73], v[164:167], v[204:207], v[70:73]
	v_mfma_f32_16x16x32_bf16 v[66:69], v[172:175], v[204:207], v[66:69]
	s_setprio 0
	s_add_i32 s4, s6, s38
	v_lshl_add_u64 v[208:209], s[34:35], 0, v[0:1]
	s_mov_b32 m0, s4
	ds_read_b128 v[176:179], v147 offset:16384
	ds_read_b128 v[180:183], v147 offset:17408
	ds_read_b128 v[184:187], v147 offset:18432
	ds_read_b128 v[188:191], v147 offset:19456
	ds_read_b128 v[192:195], v147 offset:20480
	ds_read_b128 v[196:199], v147 offset:21504
	ds_read_b128 v[200:203], v147 offset:22528
	ds_read_b128 v[204:207], v147 offset:23552
	global_load_lds_dwordx4 v[208:209], off
	s_add_i32 m0, s4, 0x2000
	s_add_u32 s4, s34, 0x40000
	v_lshl_add_u64 v[222:223], s[34:35], 0, v[132:133]
	s_addc_u32 s5, s35, 0
	s_add_i32 s6, s7, s38
	global_load_lds_dwordx4 v[222:223], off
	v_lshl_add_u64 v[224:225], s[4:5], 0, v[0:1]
	s_mov_b32 m0, s6
	v_lshl_add_u64 v[226:227], s[36:37], 0, v[130:131]
	global_load_lds_dwordx4 v[224:225], off
	v_lshl_add_u64 v[224:225], s[4:5], 0, v[132:133]
	s_add_i32 m0, s6, 0x2000
	s_nop 0
	global_load_lds_dwordx4 v[224:225], off
	v_lshl_add_u64 v[224:225], s[36:37], 0, v[134:135]
	s_mov_b32 m0, s43
	s_nop 0
	global_load_lds_dwordx4 v[224:225], off
	s_mov_b32 m0, s44
	s_nop 0
	global_load_lds_dwordx4 v[226:227], off
	s_waitcnt vmcnt(8)
	s_waitcnt lgkmcnt(0)
	s_barrier
	s_setprio 1
	s_waitcnt lgkmcnt(0)
	v_mfma_f32_16x16x32_bf16 v[62:65], v[140:143], v[176:179], v[62:65]
	v_mfma_f32_16x16x32_bf16 v[58:61], v[152:155], v[176:179], v[58:61]
	v_mfma_f32_16x16x32_bf16 v[54:57], v[140:143], v[184:187], v[54:57]
	v_mfma_f32_16x16x32_bf16 v[46:49], v[152:155], v[184:187], v[46:49]
	v_mfma_f32_16x16x32_bf16 v[38:41], v[140:143], v[192:195], v[38:41]
	v_mfma_f32_16x16x32_bf16 v[30:33], v[152:155], v[192:195], v[30:33]
	v_mfma_f32_16x16x32_bf16 v[22:25], v[140:143], v[200:203], v[22:25]
	v_mfma_f32_16x16x32_bf16 v[14:17], v[152:155], v[200:203], v[14:17]
	v_mfma_f32_16x16x32_bf16 v[62:65], v[148:151], v[180:183], v[62:65]
	v_mfma_f32_16x16x32_bf16 v[58:61], v[156:159], v[180:183], v[58:61]
	v_mfma_f32_16x16x32_bf16 v[54:57], v[148:151], v[188:191], v[54:57]
	v_mfma_f32_16x16x32_bf16 v[46:49], v[156:159], v[188:191], v[46:49]
	v_mfma_f32_16x16x32_bf16 v[38:41], v[148:151], v[196:199], v[38:41]
	v_mfma_f32_16x16x32_bf16 v[30:33], v[156:159], v[196:199], v[30:33]
	v_mfma_f32_16x16x32_bf16 v[22:25], v[148:151], v[204:207], v[22:25]
	v_mfma_f32_16x16x32_bf16 v[14:17], v[156:159], v[204:207], v[14:17]
	s_setprio 0
	s_setprio 1
	v_mfma_f32_16x16x32_bf16 v[50:53], v[160:163], v[176:179], v[50:53]
	v_mfma_f32_16x16x32_bf16 v[42:45], v[168:171], v[176:179], v[42:45]
	v_mfma_f32_16x16x32_bf16 v[34:37], v[160:163], v[184:187], v[34:37]
	v_mfma_f32_16x16x32_bf16 v[26:29], v[168:171], v[184:187], v[26:29]
	v_mfma_f32_16x16x32_bf16 v[18:21], v[160:163], v[192:195], v[18:21]
	v_mfma_f32_16x16x32_bf16 v[10:13], v[168:171], v[192:195], v[10:13]
	v_mfma_f32_16x16x32_bf16 v[6:9], v[160:163], v[200:203], v[6:9]
	v_mfma_f32_16x16x32_bf16 v[2:5], v[168:171], v[200:203], v[2:5]
	v_mfma_f32_16x16x32_bf16 v[50:53], v[164:167], v[180:183], v[50:53]
	v_mfma_f32_16x16x32_bf16 v[42:45], v[172:175], v[180:183], v[42:45]
	v_mfma_f32_16x16x32_bf16 v[34:37], v[164:167], v[188:191], v[34:37]
	v_mfma_f32_16x16x32_bf16 v[26:29], v[172:175], v[188:191], v[26:29]
	s_barrier
	s_setprio 3
	v_mfma_f32_16x16x32_bf16 v[18:21], v[164:167], v[196:199], v[18:21]
	v_mfma_f32_16x16x32_bf16 v[10:13], v[172:175], v[196:199], v[10:13]
	v_mfma_f32_16x16x32_bf16 v[6:9], v[164:167], v[204:207], v[6:9]
	v_mfma_f32_16x16x32_bf16 v[2:5], v[172:175], v[204:207], v[2:5]
	s_setprio 0
	s_add_i32 s6, 0, 0x18000
	s_add_i32 s7, 0, 0x1c000
	v_add_u32_e32 v156, s6, v146
	v_add_u32_e32 v172, s7, v146
	ds_read_b128 v[140:143], v156
	ds_read_b128 v[148:151], v156 offset:1024
	ds_read_b128 v[152:155], v156 offset:2048
	ds_read_b128 v[156:159], v156 offset:3072
	ds_read_b128 v[160:163], v172
	ds_read_b128 v[164:167], v172 offset:1024
	ds_read_b128 v[168:171], v172 offset:2048
	ds_read_b128 v[172:175], v172 offset:3072
	s_add_u32 s4, s36, 0x40000
	s_addc_u32 s5, s37, 0
	s_mov_b32 m0, s45
	v_lshl_add_u64 v[228:229], s[4:5], 0, v[134:135]
	ds_read_b128 v[176:179], v147 offset:32768
	ds_read_b128 v[180:183], v147 offset:33792
	ds_read_b128 v[184:187], v147 offset:34816
	ds_read_b128 v[188:191], v147 offset:35840
	ds_read_b128 v[192:195], v147 offset:36864
	ds_read_b128 v[196:199], v147 offset:37888
	ds_read_b128 v[200:203], v147 offset:38912
	ds_read_b128 v[204:207], v147 offset:39936
	global_load_lds_dwordx4 v[228:229], off
	v_lshl_add_u64 v[228:229], s[4:5], 0, v[130:131]
	s_mov_b32 m0, s46
	s_nop 0
	global_load_lds_dwordx4 v[228:229], off
	s_waitcnt vmcnt(8)
	s_waitcnt lgkmcnt(0)
	s_barrier
	s_setprio 1
	s_waitcnt lgkmcnt(0)
	v_mfma_f32_16x16x32_bf16 v[126:129], v[140:143], v[176:179], v[126:129]
	v_mfma_f32_16x16x32_bf16 v[122:125], v[152:155], v[176:179], v[122:125]
	v_mfma_f32_16x16x32_bf16 v[118:121], v[140:143], v[184:187], v[118:121]
	v_mfma_f32_16x16x32_bf16 v[110:113], v[152:155], v[184:187], v[110:113]
	v_mfma_f32_16x16x32_bf16 v[102:105], v[140:143], v[192:195], v[102:105]
	v_mfma_f32_16x16x32_bf16 v[94:97], v[152:155], v[192:195], v[94:97]
	v_mfma_f32_16x16x32_bf16 v[86:89], v[140:143], v[200:203], v[86:89]
	v_mfma_f32_16x16x32_bf16 v[78:81], v[152:155], v[200:203], v[78:81]
	v_mfma_f32_16x16x32_bf16 v[126:129], v[148:151], v[180:183], v[126:129]
	v_mfma_f32_16x16x32_bf16 v[122:125], v[156:159], v[180:183], v[122:125]
	v_mfma_f32_16x16x32_bf16 v[118:121], v[148:151], v[188:191], v[118:121]
	v_mfma_f32_16x16x32_bf16 v[110:113], v[156:159], v[188:191], v[110:113]
	v_mfma_f32_16x16x32_bf16 v[102:105], v[148:151], v[196:199], v[102:105]
	v_mfma_f32_16x16x32_bf16 v[94:97], v[156:159], v[196:199], v[94:97]
	v_mfma_f32_16x16x32_bf16 v[86:89], v[148:151], v[204:207], v[86:89]
	v_mfma_f32_16x16x32_bf16 v[78:81], v[156:159], v[204:207], v[78:81]
	s_setprio 0
	s_setprio 1
	v_mfma_f32_16x16x32_bf16 v[114:117], v[160:163], v[176:179], v[114:117]
	v_mfma_f32_16x16x32_bf16 v[106:109], v[168:171], v[176:179], v[106:109]
	v_mfma_f32_16x16x32_bf16 v[98:101], v[160:163], v[184:187], v[98:101]
	v_mfma_f32_16x16x32_bf16 v[90:93], v[168:171], v[184:187], v[90:93]
	v_mfma_f32_16x16x32_bf16 v[82:85], v[160:163], v[192:195], v[82:85]
	v_mfma_f32_16x16x32_bf16 v[74:77], v[168:171], v[192:195], v[74:77]
	v_mfma_f32_16x16x32_bf16 v[70:73], v[160:163], v[200:203], v[70:73]
	v_mfma_f32_16x16x32_bf16 v[66:69], v[168:171], v[200:203], v[66:69]
	v_mfma_f32_16x16x32_bf16 v[114:117], v[164:167], v[180:183], v[114:117]
	v_mfma_f32_16x16x32_bf16 v[106:109], v[172:175], v[180:183], v[106:109]
	v_mfma_f32_16x16x32_bf16 v[98:101], v[164:167], v[188:191], v[98:101]
	v_mfma_f32_16x16x32_bf16 v[90:93], v[172:175], v[188:191], v[90:93]
	s_barrier
	s_setprio 3
	v_mfma_f32_16x16x32_bf16 v[82:85], v[164:167], v[196:199], v[82:85]
	v_mfma_f32_16x16x32_bf16 v[74:77], v[172:175], v[196:199], v[74:77]
	v_mfma_f32_16x16x32_bf16 v[70:73], v[164:167], v[204:207], v[70:73]
	v_mfma_f32_16x16x32_bf16 v[66:69], v[172:175], v[204:207], v[66:69]
	s_setprio 0
	s_add_i32 s4, s6, s38
	v_lshl_add_u64 v[208:209], v[208:209], 0, s[82:83]
	s_mov_b32 m0, s4
	ds_read_b128 v[176:179], v147 offset:49152
	ds_read_b128 v[180:183], v147 offset:50176
	ds_read_b128 v[184:187], v147 offset:51200
	ds_read_b128 v[188:191], v147 offset:52224
	ds_read_b128 v[192:195], v147 offset:53248
	ds_read_b128 v[196:199], v147 offset:54272
	ds_read_b128 v[200:203], v147 offset:55296
	ds_read_b128 v[204:207], v147 offset:56320
	global_load_lds_dwordx4 v[208:209], off
	s_add_i32 m0, s4, 0x2000
	s_add_u32 s4, s34, 0x40080
	v_lshl_add_u64 v[208:209], v[222:223], 0, s[82:83]
	s_addc_u32 s5, s35, 0
	s_add_i32 s6, s7, s38
	global_load_lds_dwordx4 v[208:209], off
	v_lshl_add_u64 v[208:209], s[4:5], 0, v[0:1]
	s_mov_b32 m0, s6
	s_nop 0
	global_load_lds_dwordx4 v[208:209], off
	v_lshl_add_u64 v[208:209], s[4:5], 0, v[132:133]
	s_add_i32 m0, s6, 0x2000
	s_nop 0
	global_load_lds_dwordx4 v[208:209], off
	v_lshl_add_u64 v[208:209], v[224:225], 0, s[82:83]
	s_mov_b32 m0, s49
	s_nop 0
	global_load_lds_dwordx4 v[208:209], off
	v_lshl_add_u64 v[208:209], v[226:227], 0, s[82:83]
	s_mov_b32 m0, s50
	s_nop 0
	global_load_lds_dwordx4 v[208:209], off
	s_waitcnt vmcnt(8)
	s_waitcnt lgkmcnt(0)
	s_barrier
	s_setprio 1
	s_waitcnt lgkmcnt(0)
	v_mfma_f32_16x16x32_bf16 v[62:65], v[140:143], v[176:179], v[62:65]
	v_mfma_f32_16x16x32_bf16 v[58:61], v[152:155], v[176:179], v[58:61]
	v_mfma_f32_16x16x32_bf16 v[54:57], v[140:143], v[184:187], v[54:57]
	v_mfma_f32_16x16x32_bf16 v[46:49], v[152:155], v[184:187], v[46:49]
	v_mfma_f32_16x16x32_bf16 v[38:41], v[140:143], v[192:195], v[38:41]
	v_mfma_f32_16x16x32_bf16 v[30:33], v[152:155], v[192:195], v[30:33]
	v_mfma_f32_16x16x32_bf16 v[22:25], v[140:143], v[200:203], v[22:25]
	v_mfma_f32_16x16x32_bf16 v[14:17], v[152:155], v[200:203], v[14:17]
	v_mfma_f32_16x16x32_bf16 v[62:65], v[148:151], v[180:183], v[62:65]
	v_mfma_f32_16x16x32_bf16 v[58:61], v[156:159], v[180:183], v[58:61]
	v_mfma_f32_16x16x32_bf16 v[54:57], v[148:151], v[188:191], v[54:57]
	v_mfma_f32_16x16x32_bf16 v[46:49], v[156:159], v[188:191], v[46:49]
	v_mfma_f32_16x16x32_bf16 v[38:41], v[148:151], v[196:199], v[38:41]
	v_mfma_f32_16x16x32_bf16 v[30:33], v[156:159], v[196:199], v[30:33]
	v_mfma_f32_16x16x32_bf16 v[22:25], v[148:151], v[204:207], v[22:25]
	v_mfma_f32_16x16x32_bf16 v[14:17], v[156:159], v[204:207], v[14:17]
	s_setprio 0
	s_setprio 1
	v_mfma_f32_16x16x32_bf16 v[50:53], v[160:163], v[176:179], v[50:53]
	v_mfma_f32_16x16x32_bf16 v[42:45], v[168:171], v[176:179], v[42:45]
	v_mfma_f32_16x16x32_bf16 v[34:37], v[160:163], v[184:187], v[34:37]
	v_mfma_f32_16x16x32_bf16 v[26:29], v[168:171], v[184:187], v[26:29]
	v_mfma_f32_16x16x32_bf16 v[18:21], v[160:163], v[192:195], v[18:21]
	v_mfma_f32_16x16x32_bf16 v[10:13], v[168:171], v[192:195], v[10:13]
	v_mfma_f32_16x16x32_bf16 v[6:9], v[160:163], v[200:203], v[6:9]
	v_mfma_f32_16x16x32_bf16 v[2:5], v[168:171], v[200:203], v[2:5]
	v_mfma_f32_16x16x32_bf16 v[50:53], v[164:167], v[180:183], v[50:53]
	v_mfma_f32_16x16x32_bf16 v[42:45], v[172:175], v[180:183], v[42:45]
	v_mfma_f32_16x16x32_bf16 v[34:37], v[164:167], v[188:191], v[34:37]
	v_mfma_f32_16x16x32_bf16 v[26:29], v[172:175], v[188:191], v[26:29]
	s_barrier
	s_setprio 3
	v_mfma_f32_16x16x32_bf16 v[18:21], v[164:167], v[196:199], v[18:21]
	v_mfma_f32_16x16x32_bf16 v[10:13], v[172:175], v[196:199], v[10:13]
	v_mfma_f32_16x16x32_bf16 v[6:9], v[164:167], v[204:207], v[6:9]
	v_mfma_f32_16x16x32_bf16 v[2:5], v[172:175], v[204:207], v[2:5]
	s_setprio 0
	s_add_i32 s59, s59, 2
	s_add_u32 s30, s30, 0x100
	s_addc_u32 s31, s31, 0
	s_add_u32 s68, s68, 0x100
	s_addc_u32 s69, s69, 0
	s_cmp_gt_u32 s59, 13
	s_cbranch_scc0 .LBB0_489
	s_and_b64 vcc, exec, s[20:21]
	s_cbranch_vccz .LBB0_492
	s_barrier
